# P3 attention: next-unit prefetch loads no longer forced complete by the q-gain waits (vmcnt counts raised by 16 on the prefetch path)
# baseline (speedup 1.0000x reference)
.LBB0_94:
	s_cmp_gt_i32 s79, 1
	s_cselect_b64 s[0:1], -1, 0
	s_and_b64 s[2:3], s[48:49], s[0:1]
	s_andn2_b64 vcc, exec, s[2:3]
	s_cbranch_vccnz .LBB0_106
	v_lshrrev_b32_e32 v1, 20, v0
	v_lshrrev_b32_e32 v0, 10, v0
	v_or_b32_e32 v0, v0, v1
	s_movk_i32 s2, 0x3ff
	v_and_or_b32 v0, v0, s2, v254
	v_cmp_eq_u32_e32 vcc, 0, v0
	s_barrier
	s_and_saveexec_b64 s[2:3], vcc
	s_cbranch_execz .LBB0_105
	buffer_wbl2 sc1
	s_waitcnt vmcnt(0)
	s_load_dwordx2 s[4:5], s[82:83], 0x58
	v_mov_b32_e32 v2, 0
	s_mov_b64 s[6:7], exec
	v_mbcnt_lo_u32_b32 v1, s6, 0
	v_mbcnt_hi_u32_b32 v1, s7, v1
	s_waitcnt lgkmcnt(0)
	global_load_dword v0, v2, s[4:5] offset:40
	v_cmp_eq_u32_e32 vcc, 0, v1
	s_and_saveexec_b64 s[8:9], vcc
	s_cbranch_execz .LBB0_98
	s_bcnt1_i32_b64 s6, s[6:7]
	v_mov_b32_e32 v3, s6
	global_atomic_add v3, v2, v3, s[4:5] offset:32 sc0
.LBB0_98:
	s_or_b64 exec, exec, s[8:9]
	s_waitcnt vmcnt(0)
	v_readfirstlane_b32 s6, v3
	v_add_u32_e32 v2, -1, v0
	s_nop 0
	v_add_u32_e32 v1, s6, v1
	v_cmp_eq_u32_sdwa s[8:9], v1, v2 src0_sel:WORD_0 src1_sel:DWORD
	s_and_saveexec_b64 s[6:7], s[8:9]
	s_cbranch_execz .LBB0_101
	s_mov_b64 s[8:9], exec
	v_mbcnt_lo_u32_b32 v2, s8, 0
	v_mbcnt_hi_u32_b32 v2, s9, v2
	v_cmp_eq_u32_e32 vcc, 0, v2
	s_and_b64 s[10:11], exec, vcc
	s_mov_b64 exec, s[10:11]
	s_cbranch_execz .LBB0_101
	v_sub_u32_e32 v0, 0x10000, v0
	s_bcnt1_i32_b64 s8, s[8:9]
	v_mul_lo_u32 v0, v0, s8
	v_mov_b32_e32 v2, 0
	global_atomic_add v2, v0, s[4:5] offset:32
.LBB0_101:
	s_or_b64 exec, exec, s[6:7]
	v_mov_b32_e32 v0, 0
	global_load_dword v2, v0, s[4:5] offset:32 sc1
	v_and_b32_e32 v1, 0xffff0000, v1
	s_waitcnt vmcnt(0)
	v_and_b32_e32 v2, 0xffff0000, v2
	v_cmp_eq_u32_e32 vcc, v2, v1
	s_and_b64 exec, exec, vcc
	s_cbranch_execz .LBB0_104
	s_mov_b64 s[6:7], 0
.LBB0_103:
	s_sleep 1
	global_load_dword v2, v0, s[4:5] offset:32 sc1
	s_waitcnt vmcnt(0)
	v_and_b32_e32 v2, 0xffff0000, v2
	v_cmp_ne_u32_e32 vcc, v2, v1
	s_or_b64 s[6:7], vcc, s[6:7]
	s_andn2_b64 exec, exec, s[6:7]
	s_cbranch_execnz .LBB0_103
.LBB0_104:
	buffer_inv sc1
.LBB0_105:
	s_or_b64 exec, exec, s[2:3]
	s_barrier

.LBB0_398:
	s_or_b64 exec, exec, s[2:3]
	v_pk_mul_f32 v[10:11], v[8:9], v[10:11] op_sel_hi:[0,1]
	v_pk_mul_f32 v[4:5], v[4:5], v[10:11]
	v_pk_mul_f32 v[10:11], v[8:9], v[14:15] op_sel_hi:[0,1]
	v_pk_mul_f32 v[6:7], v[6:7], v[10:11]
	v_cvt_pk_bf16_f32 v4, v4, v5
	v_cvt_pk_bf16_f32 v5, v6, v7
	v_pk_mul_f32 v[6:7], v[8:9], v[16:17] op_sel_hi:[0,1]
	v_pk_mul_f32 v[0:1], v[0:1], v[6:7]
	v_and_b32_e32 v35, 0xffff0000, v143
	v_cvt_pk_bf16_f32 v6, v0, v1
	v_pk_mul_f32 v[0:1], v[8:9], v[18:19] op_sel_hi:[0,1]
	v_pk_mul_f32 v[0:1], v[2:3], v[0:1]
	v_lshlrev_b32_e32 v34, 16, v142
	v_cvt_pk_bf16_f32 v7, v0, v1
	ds_write_b128 v172, v[4:7] offset:18432
	ds_write_b128 v170, v[124:127] offset:64512
	v_lshl_add_u64 v[4:5], s[0:1], 2, v[150:151]
	global_load_dwordx4 v[24:27], v[4:5], off offset:16
	global_load_dwordx4 v[28:31], v[4:5], off
	global_load_dwordx4 v[16:19], v[4:5], off offset:80
	global_load_dwordx4 v[20:23], v[4:5], off offset:64
	global_load_dwordx4 v[8:11], v[4:5], off offset:144
	s_waitcnt lgkmcnt(4)
	global_load_dwordx4 v[12:15], v[4:5], off offset:128
	global_load_dwordx4 v[0:3], v[4:5], off offset:208
	s_nop 0
	global_load_dwordx4 v[4:7], v[4:5], off offset:192
	v_and_b32_e32 v39, 0xffff0000, v142
	v_mov_b32_e32 v38, v35
	v_and_b32_e32 v59, 0xffff0000, v141
	v_lshlrev_b32_e32 v32, 16, v143
	v_mov_b32_e32 v33, v34
	v_pk_mul_f32 v[36:37], v[38:39], v[38:39]
	v_lshlrev_b32_e32 v38, 16, v140
	v_and_b32_e32 v43, 0xffff0000, v140
	v_mov_b32_e32 v42, v59
	v_and_b32_e32 v57, 0xffff0000, v139
	v_pk_fma_f32 v[70:71], v[32:33], v[32:33], v[36:37]
	v_lshlrev_b32_e32 v36, 16, v141
	v_mov_b32_e32 v37, v38
	v_pk_mul_f32 v[40:41], v[42:43], v[42:43]
	v_lshlrev_b32_e32 v42, 16, v138
	v_and_b32_e32 v61, 0xffff0000, v138
	v_mov_b32_e32 v60, v57
	v_lshlrev_b32_e32 v66, 16, v129
	v_and_b32_e32 v67, 0xffff0000, v129
	v_lshlrev_b32_e32 v68, 16, v128
	v_and_b32_e32 v69, 0xffff0000, v128
	v_pk_fma_f32 v[72:73], v[36:37], v[36:37], v[40:41]
	v_lshlrev_b32_e32 v40, 16, v139
	v_mov_b32_e32 v41, v42
	v_pk_mul_f32 v[44:45], v[60:61], v[60:61]
	v_lshlrev_b32_e32 v64, 16, v130
	v_and_b32_e32 v65, 0xffff0000, v130
	v_pk_mul_f32 v[186:187], v[66:67], v[66:67]
	v_pk_mul_f32 v[188:189], v[68:69], v[68:69]
	v_pk_fma_f32 v[74:75], v[40:41], v[40:41], v[44:45]
	v_lshlrev_b32_e32 v62, 16, v131
	v_and_b32_e32 v63, 0xffff0000, v131
	v_pk_mul_f32 v[184:185], v[64:65], v[64:65]
	v_add_f32_e32 v37, v186, v187
	v_add_f32_e32 v41, v188, v189
	v_lshlrev_b32_e32 v54, 16, v132
	v_and_b32_e32 v55, 0xffff0000, v132
	v_pk_mul_f32 v[182:183], v[62:63], v[62:63]
	v_add_f32_e32 v37, v41, v37
	v_add_f32_e32 v41, v184, v185
	v_lshlrev_b32_e32 v52, 16, v133
	v_and_b32_e32 v53, 0xffff0000, v133
	v_pk_mul_f32 v[180:181], v[54:55], v[54:55]
	v_add_f32_e32 v33, v182, v183
	v_add_f32_e32 v37, v41, v37
	v_lshlrev_b32_e32 v50, 16, v134
	v_and_b32_e32 v51, 0xffff0000, v134
	v_pk_mul_f32 v[178:179], v[52:53], v[52:53]
	v_add_f32_e32 v33, v33, v37
	v_add_f32_e32 v37, v180, v181
	v_lshlrev_b32_e32 v48, 16, v135
	v_and_b32_e32 v49, 0xffff0000, v135
	v_pk_mul_f32 v[176:177], v[50:51], v[50:51]
	v_add_f32_e32 v33, v37, v33
	v_add_f32_e32 v37, v178, v179
	v_lshlrev_b32_e32 v46, 16, v136
	v_and_b32_e32 v47, 0xffff0000, v136
	v_pk_mul_f32 v[174:175], v[48:49], v[48:49]
	v_add_f32_e32 v33, v37, v33
	v_add_f32_e32 v37, v176, v177
	v_lshlrev_b32_e32 v44, 16, v137
	v_and_b32_e32 v45, 0xffff0000, v137
	v_pk_mul_f32 v[78:79], v[46:47], v[46:47]
	v_add_f32_e32 v33, v37, v33
	v_add_f32_e32 v37, v174, v175
	v_pk_mul_f32 v[76:77], v[44:45], v[44:45]
	v_add_f32_e32 v33, v37, v33
	v_add_f32_e32 v37, v78, v79
	v_add_f32_e32 v33, v37, v33
	v_add_f32_e32 v37, v76, v77
	v_add_f32_e32 v33, v37, v33
	v_add_f32_e32 v33, v75, v33
	v_add_f32_e32 v33, v74, v33
	v_add_f32_e32 v33, v73, v33
	v_add_f32_e32 v33, v72, v33
	v_add_f32_e32 v33, v71, v33
	v_add_f32_e32 v33, v70, v33
	ds_bpermute_b32 v37, v160, v33
	s_add_i32 s20, s20, s70
	s_cmpk_gt_i32 s20, 0x11ff
	s_cselect_b64 s[0:1], -1, 0
	s_and_b64 vcc, exec, s[0:1]
	s_cbranch_vccnz .Lp3_nopf
	s_add_i32 s2, s20, 0xfffff400
	s_lshr_b32 s2, s2, 4
	s_ashr_i32 s3, s20, 5
	s_cmpk_lt_i32 s20, 0xc00
	s_cselect_b32 s2, s3, s2
	s_mul_hi_i32 s3, s2, 0x2aaaaaab
	s_lshr_b32 s8, s3, 31
	s_ashr_i32 s3, s3, 1
	s_add_i32 s3, s3, s8
	s_lshl_b32 s8, s3, 12
	s_add_i32 s8, s8, 0x10000
	s_lshl_b32 s9, s3, 13
	s_cmpk_lt_i32 s20, 0xc00
	s_mul_i32 s3, s3, 12
	s_cselect_b32 s39, 31, 15
	s_cselect_b32 s40, s22, 0x1000
	s_cselect_b32 s41, 5, 4
	s_cselect_b32 s8, s9, s8
	s_sub_i32 s2, s2, s3
	s_ashr_i32 s3, s2, 1
	s_and_b32 s9, s39, s20
	s_and_b32 s39, s3, -2
	s_lshr_b32 s3, s40, s39
	s_lshr_b32 s40, s3, 8
	s_sub_i32 s41, s41, s39
	s_add_i32 s40, s40, -1
	s_lshr_b32 s41, s9, s41
	s_and_b32 s9, s40, s9
	s_lshl_b32 s42, s9, 8
	v_add_u32_e32 v41, s42, v153
	s_add_i32 s43, s3, -1
	v_min_i32_e32 v56, s43, v41
	v_cmp_lt_i32_e32 vcc, -1, v41
	s_lshl_b32 s2, s2, 6
	s_ashr_i32 s3, s2, 31
	v_cndmask_b32_e32 v72, 0, v56, vcc
	v_ashrrev_i32_e32 v73, 31, v72
	s_ashr_i32 s9, s8, 31
	s_or_b32 s8, s8, s41
	s_lshl_b64 s[2:3], s[2:3], 1
	v_lshlrev_b64 v[72:73], s39, v[72:73]
	v_lshl_add_u64 v[70:71], v[146:147], 0, s[2:3]
	v_lshl_add_u64 v[72:73], v[72:73], 0, s[8:9]
	v_mad_u64_u32 v[74:75], s[40:41], v72, s21, v[70:71]
	v_mov_b32_e32 v56, v75
	v_mad_u64_u32 v[72:73], s[40:41], v73, s21, v[56:57]
	v_add_u32_e32 v56, s42, v152
	v_min_i32_e32 v58, s43, v56
	v_cmp_lt_i32_e32 vcc, -1, v56
	v_mov_b32_e32 v75, v72
	global_load_dwordx4 v[80:83], v[74:75], off offset:1536
	global_load_dwordx4 v[84:87], v[74:75], off offset:3072
	v_cndmask_b32_e32 v72, 0, v58, vcc
	v_ashrrev_i32_e32 v73, 31, v72
	v_lshlrev_b64 v[72:73], s39, v[72:73]
	v_lshl_add_u64 v[72:73], v[72:73], 0, s[8:9]
	v_mad_u64_u32 v[74:75], s[40:41], v72, s21, v[70:71]
	v_mov_b32_e32 v56, v75
	v_mad_u64_u32 v[72:73], s[40:41], v73, s21, v[56:57]
	v_add_u32_e32 v56, 0x80, v41
	v_min_i32_e32 v56, s43, v56
	v_cmp_lt_i32_e32 vcc, s23, v41
	v_mov_b32_e32 v75, v72
	global_load_dwordx4 v[88:91], v[74:75], off offset:1536
	global_load_dwordx4 v[92:95], v[74:75], off offset:3072
	v_cndmask_b32_e32 v72, 0, v56, vcc
	v_ashrrev_i32_e32 v73, 31, v72
	v_lshlrev_b64 v[72:73], s39, v[72:73]
	v_lshl_add_u64 v[72:73], v[72:73], 0, s[8:9]
	v_mad_u64_u32 v[74:75], s[40:41], v72, s21, v[70:71]
	v_mov_b32_e32 v56, v75
	v_mad_u64_u32 v[72:73], s[40:41], v73, s21, v[56:57]
	v_add_u32_e32 v56, 0xc0, v41
	v_min_i32_e32 v56, s43, v56
	v_cmp_lt_i32_e32 vcc, s26, v41
	v_mov_b32_e32 v75, v72
	global_load_dwordx4 v[96:99], v[74:75], off offset:1536
	global_load_dwordx4 v[100:103], v[74:75], off offset:3072
	v_cndmask_b32_e32 v72, 0, v56, vcc
	v_ashrrev_i32_e32 v73, 31, v72
	v_lshlrev_b64 v[72:73], s39, v[72:73]
	v_lshl_add_u64 v[72:73], v[72:73], 0, s[8:9]
	v_mad_u64_u32 v[74:75], s[40:41], v72, s21, v[70:71]
	v_mov_b32_e32 v56, v75
	v_mad_u64_u32 v[72:73], s[40:41], v73, s21, v[56:57]
	v_add_u32_e32 v56, 0x100, v41
	v_min_i32_e32 v56, s43, v56
	v_cmp_lt_i32_e32 vcc, s27, v41
	v_mov_b32_e32 v75, v72
	global_load_dwordx4 v[104:107], v[74:75], off offset:1536
	global_load_dwordx4 v[108:111], v[74:75], off offset:3072
	v_cndmask_b32_e32 v72, 0, v56, vcc
	v_ashrrev_i32_e32 v73, 31, v72
	v_lshlrev_b64 v[72:73], s39, v[72:73]
	v_lshl_add_u64 v[72:73], v[72:73], 0, s[8:9]
	v_mad_u64_u32 v[74:75], s[40:41], v72, s21, v[70:71]
	v_mov_b32_e32 v56, v75
	v_mad_u64_u32 v[72:73], s[40:41], v73, s21, v[56:57]
	v_add_u32_e32 v56, 0x140, v41
	v_min_i32_e32 v56, s43, v56
	v_cmp_lt_i32_e32 vcc, s28, v41
	v_mov_b32_e32 v75, v72
	global_load_dwordx4 v[112:115], v[74:75], off offset:1536
	global_load_dwordx4 v[116:119], v[74:75], off offset:3072
	v_cndmask_b32_e32 v72, 0, v56, vcc
	v_ashrrev_i32_e32 v73, 31, v72
	v_lshlrev_b64 v[72:73], s39, v[72:73]
	v_lshl_add_u64 v[72:73], v[72:73], 0, s[8:9]
	v_mad_u64_u32 v[70:71], s[40:41], v72, s21, v[70:71]
	v_mov_b32_e32 v56, v71
	v_mad_u64_u32 v[72:73], s[40:41], v73, s21, v[56:57]
	v_mov_b32_e32 v71, v72
	global_load_dwordx4 v[120:123], v[70:71], off offset:1536
	global_load_dwordx4 v[124:127], v[70:71], off offset:3072
	v_add_u32_e32 v70, s42, v155
	v_ashrrev_i32_e32 v71, 31, v70
	v_lshlrev_b64 v[70:71], s39, v[70:71]
	v_lshl_add_u64 v[70:71], v[70:71], 0, s[8:9]
	v_mov_b64_e32 v[72:73], s[16:17]
	v_mad_u64_u32 v[72:73], s[8:9], v70, s21, v[72:73]
	v_mov_b32_e32 v56, v73
	v_mad_u64_u32 v[70:71], s[8:9], v71, s21, v[56:57]
	v_mov_b32_e32 v73, v70
	v_lshl_add_u64 v[70:71], v[72:73], 0, s[2:3]
	v_lshl_add_u64 v[70:71], v[70:71], 0, v[144:145]
	global_load_dwordx4 v[128:131], v[70:71], off
	global_load_dwordx4 v[132:135], v[70:71], off offset:32
	global_load_dwordx4 v[136:139], v[70:71], off offset:64
	global_load_dwordx4 v[140:143], v[70:71], off offset:96
	s_branch .LBB0_400

.LBB0_400:
	s_waitcnt lgkmcnt(0)
	v_add_f32_e32 v33, v33, v37
	v_fmamk_f32 v33, v33, 0x3c800000, v165
	v_mul_f32_e32 v37, 0x4f800000, v33
	v_cmp_gt_f32_e32 vcc, s10, v33
	s_barrier
	s_nop 0
	v_cndmask_b32_e32 v41, v33, v37, vcc
	v_sqrt_f32_e32 v56, v41
	v_mov_b32_e32 v33, v35
	v_mov_b32_e32 v35, v39
	v_mov_b32_e32 v37, v59
	v_add_u32_e32 v39, -1, v56
	v_fma_f32 v58, -v39, v56, v41
	v_cmp_ge_f32_e64 s[8:9], 0, v58
	v_add_u32_e32 v58, 1, v56
	s_nop 0
	v_cndmask_b32_e64 v39, v56, v39, s[8:9]
	v_fma_f32 v56, -v58, v56, v41
	v_cmp_lt_f32_e64 s[8:9], 0, v56
	s_and_b64 s[2:3], s[4:5], exec
	s_mul_i32 s14, s14, 0x18000
	v_cndmask_b32_e64 v39, v39, v58, s[8:9]
	v_mul_f32_e32 v56, 0x37800000, v39
	v_cndmask_b32_e32 v39, v39, v56, vcc
	v_cmp_class_f32_e32 vcc, v41, v166
	s_nop 1
	v_cndmask_b32_e32 v56, v39, v41, vcc
	v_div_scale_f32 v58, s[2:3], v56, v56, s11
	v_rcp_f32_e32 v59, v58
	v_mov_b32_e32 v41, v57
	v_mov_b32_e32 v39, v43
	v_mov_b32_e32 v43, v61
	v_fma_f32 v57, -v58, v59, 1.0
	v_fmac_f32_e32 v59, v57, v59
	v_div_scale_f32 v57, vcc, s11, v56, s11
	v_mul_f32_e32 v60, v57, v59
	v_fma_f32 v61, -v58, v60, v57
	v_fmac_f32_e32 v60, v61, v59
	v_fma_f32 v57, -v58, v60, v57
	v_div_fmas_f32 v57, v57, v59, v60
	v_div_fixup_f32 v56, v57, v56, s11
	s_waitcnt vmcnt(23)
	v_pk_mul_f32 v[24:25], v[24:25], v[56:57] op_sel_hi:[1,0]
	v_pk_mul_f32 v[26:27], v[26:27], v[56:57] op_sel_hi:[1,0]
	v_pk_mul_f32 v[24:25], v[24:25], v[64:65]
	s_waitcnt vmcnt(20)
	v_pk_mul_f32 v[20:21], v[20:21], v[56:57] op_sel_hi:[1,0]
	v_cvt_pk_bf16_f32 v176, v24, v25
	v_pk_mul_f32 v[24:25], v[26:27], v[62:63]
	v_pk_mul_f32 v[22:23], v[22:23], v[56:57] op_sel_hi:[1,0]
	v_cvt_pk_bf16_f32 v177, v24, v25
	v_pk_mul_f32 v[24:25], v[18:19], v[56:57] op_sel_hi:[1,0]
	v_pk_mul_f32 v[16:17], v[16:17], v[56:57] op_sel_hi:[1,0]
	v_pk_mul_f32 v[18:19], v[20:21], v[54:55]
	v_pk_mul_f32 v[16:17], v[16:17], v[50:51]
	v_cvt_pk_bf16_f32 v178, v18, v19
	v_pk_mul_f32 v[18:19], v[22:23], v[52:53]
	v_cvt_pk_bf16_f32 v180, v16, v17
	v_cvt_pk_bf16_f32 v179, v18, v19
	ds_read_b128 v[16:19], v171 offset:9216
	v_pk_mul_f32 v[28:29], v[28:29], v[56:57] op_sel_hi:[1,0]
	v_pk_mul_f32 v[30:31], v[30:31], v[56:57] op_sel_hi:[1,0]
	v_pk_mul_f32 v[28:29], v[28:29], v[68:69]
	v_pk_mul_f32 v[20:21], v[24:25], v[48:49]
	v_cvt_pk_bf16_f32 v174, v28, v29
	v_pk_mul_f32 v[28:29], v[30:31], v[66:67]
	v_cvt_pk_bf16_f32 v181, v20, v21
	v_cvt_pk_bf16_f32 v175, v28, v29
	s_waitcnt vmcnt(19)
	v_pk_mul_f32 v[20:21], v[10:11], v[56:57] op_sel_hi:[1,0]
	v_pk_mul_f32 v[22:23], v[8:9], v[56:57] op_sel_hi:[1,0]
	ds_read_b128 v[8:11], v171 offset:9248
	s_waitcnt lgkmcnt(1)
	v_mfma_f32_32x32x16_bf16 v[64:79], v[16:19], v[174:177], 0
	s_waitcnt vmcnt(18)
	v_mul_f32_e64 v12, v12, v56
	v_mul_f32_e64 v13, v13, v56
	v_mul_f32_e64 v14, v14, v56
	v_mul_f32_e64 v15, v15, v56
	v_pk_mul_f32 v[12:13], v[12:13], v[46:47]
	v_pk_mul_f32 v[16:17], v[20:21], v[40:41]
	v_cvt_pk_bf16_f32 v182, v12, v13
	v_pk_mul_f32 v[12:13], v[14:15], v[44:45]
	v_cvt_pk_bf16_f32 v185, v16, v17
	v_cvt_pk_bf16_f32 v183, v12, v13
	v_pk_mul_f32 v[12:13], v[22:23], v[42:43]
	s_waitcnt lgkmcnt(0)
	v_mfma_f32_32x32x16_bf16 v[64:79], v[8:11], v[178:181], v[64:79]
	v_cvt_pk_bf16_f32 v184, v12, v13
	ds_read_b128 v[12:15], v171 offset:9280
	s_waitcnt vmcnt(17)
	v_mul_f32_e64 v8, v56, v2
	v_mul_f32_e64 v9, v56, v3
	v_pk_mul_f32 v[10:11], v[56:57], v[0:1] op_sel_hi:[0,1]
	ds_read_b128 v[0:3], v171 offset:9312
	s_waitcnt vmcnt(16)
	v_pk_mul_f32 v[4:5], v[4:5], v[56:57] op_sel_hi:[1,0]
	v_pk_mul_f32 v[6:7], v[6:7], v[56:57] op_sel_hi:[1,0]
	s_waitcnt lgkmcnt(1)
	v_mfma_f32_32x32x16_bf16 v[64:79], v[12:15], v[182:185], v[64:79]
	v_mul_f32_e64 v4, v4, v38
	v_mul_f32_e64 v5, v5, v39
	s_cselect_b32 s2, 5, 4
	v_cvt_pk_bf16_f32 v186, v4, v5
	v_mul_f32_e64 v4, v6, v36
	v_mul_f32_e64 v5, v7, v37
	s_sub_i32 s2, s2, s30
	v_cvt_pk_bf16_f32 v187, v4, v5
	v_pk_mul_f32 v[4:5], v[10:11], v[34:35]
	s_and_b32 s8, s33, 3
	v_cvt_pk_bf16_f32 v188, v4, v5
	v_pk_mul_f32 v[4:5], v[8:9], v[32:33]
	s_lshl_b32 s3, s34, 12
	v_cvt_pk_bf16_f32 v189, v4, v5
	s_mulk_i32 s33, 0x300
	s_lshr_b32 s2, s35, s2
	s_waitcnt lgkmcnt(0)
	v_mfma_f32_32x32x16_bf16 v[64:79], v[0:3], v[186:189], v[64:79]
	ds_read_b128 v[0:3], v171 offset:13824
	ds_read_b128 v[4:7], v171 offset:13856
	s_add_i32 s3, s3, 0x10000
	s_lshl_b32 s9, s34, 13
	s_and_b64 s[4:5], s[4:5], exec
	s_cselect_b32 s3, s9, s3
	s_cmp_eq_u32 s37, 0
	s_cselect_b32 s4, 0xffffffc0, 0
	s_waitcnt lgkmcnt(1)
	v_mfma_f32_32x32x16_bf16 v[48:63], v[0:3], v[174:177], 0
	s_sub_i32 s5, s36, s38
	s_min_i32 s5, s5, 0x180
	s_waitcnt lgkmcnt(0)
	v_mfma_f32_32x32x16_bf16 v[48:63], v[4:7], v[178:181], v[48:63]
	ds_read_b128 v[0:3], v171 offset:13888
	ds_read_b128 v[4:7], v171 offset:13920
	s_waitcnt lgkmcnt(1)
	v_mfma_f32_32x32x16_bf16 v[48:63], v[0:3], v[182:185], v[48:63]
	s_waitcnt lgkmcnt(0)
	v_mfma_f32_32x32x16_bf16 v[48:63], v[4:7], v[186:189], v[48:63]
	ds_read_b128 v[0:3], v171 offset:18432
	ds_read_b128 v[4:7], v171 offset:18464
	s_waitcnt lgkmcnt(1)
	v_mfma_f32_32x32x16_bf16 v[32:47], v[0:3], v[174:177], 0
	s_waitcnt lgkmcnt(0)
	v_mfma_f32_32x32x16_bf16 v[32:47], v[4:7], v[178:181], v[32:47]
	ds_read_b128 v[0:3], v171 offset:18496
	ds_read_b128 v[4:7], v171 offset:18528
	s_waitcnt lgkmcnt(1)
	v_mfma_f32_32x32x16_bf16 v[32:47], v[0:3], v[182:185], v[32:47]
	s_waitcnt lgkmcnt(0)
	v_mfma_f32_32x32x16_bf16 v[32:47], v[4:7], v[186:189], v[32:47]
	ds_read_b128 v[0:3], v171 offset:23040
	ds_read_b128 v[4:7], v171 offset:23072
	s_waitcnt lgkmcnt(1)
	v_mfma_f32_32x32x16_bf16 v[16:31], v[0:3], v[174:177], 0
	s_waitcnt lgkmcnt(0)
	v_mfma_f32_32x32x16_bf16 v[16:31], v[4:7], v[178:181], v[16:31]
	ds_read_b128 v[0:3], v171 offset:23104
	ds_read_b128 v[4:7], v171 offset:23136
	ds_read_b128 v[194:197], v171 offset:27680
	s_waitcnt lgkmcnt(2)
	v_mfma_f32_32x32x16_bf16 v[16:31], v[0:3], v[182:185], v[16:31]
	ds_read_b128 v[0:3], v171 offset:27648
	ds_read_b128 v[198:201], v171 offset:27712
	ds_read_b128 v[202:205], v171 offset:27744
	s_waitcnt lgkmcnt(4)
	v_mfma_f32_32x32x16_bf16 v[16:31], v[4:7], v[186:189], v[16:31]
	s_waitcnt lgkmcnt(2)
	v_mfma_f32_32x32x16_bf16 v[0:15], v[0:3], v[174:177], 0
	v_add_u32_e32 v175, s33, v164
	ds_read2_b32 v[176:177], v175 offset0:31 offset1:32
	v_add_u32_e32 v174, s4, v154
	s_add_i32 s4, s5, s4
	v_cmp_gt_u32_e32 vcc, s4, v174
	s_waitcnt lgkmcnt(0)
	v_add_f32_e32 v64, v64, v176
	v_mfma_f32_32x32x16_bf16 v[0:15], v[194:197], v[178:181], v[0:15]
	ds_read2_b32 v[178:179], v175 offset0:33 offset1:34
	ds_read2_b32 v[180:181], v175 offset0:39 offset1:40
	ds_read2_b32 v[190:191], v175 offset0:41 offset1:42
	v_or_b32_e32 v176, 1, v174
	v_cndmask_b32_e32 v64, v173, v64, vcc
	v_add_f32_e32 v65, v65, v177
	v_cmp_gt_u32_e32 vcc, s4, v176
	v_or_b32_e32 v176, 2, v174
	s_waitcnt lgkmcnt(2)
	v_add_f32_e32 v66, v66, v178
	v_cndmask_b32_e32 v65, v173, v65, vcc
	v_cmp_gt_u32_e32 vcc, s4, v176
	v_or_b32_e32 v176, 3, v174
	v_add_f32_e32 v67, v67, v179
	v_cndmask_b32_e32 v66, v173, v66, vcc
	v_cmp_gt_u32_e32 vcc, s4, v176
	ds_read2_b32 v[178:179], v175 offset0:47 offset1:48
	v_mfma_f32_32x32x16_bf16 v[0:15], v[198:201], v[182:185], v[0:15]
	v_cndmask_b32_e32 v176, v173, v67, vcc
	s_waitcnt lgkmcnt(2)
	v_add_f32_e32 v67, v68, v180
	v_or_b32_e32 v68, 8, v174
	v_cmp_gt_u32_e32 vcc, s4, v68
	v_add_f32_e32 v68, v69, v181
	v_or_b32_e32 v69, 9, v174
	v_cndmask_b32_e32 v67, v173, v67, vcc
	v_cmp_gt_u32_e32 vcc, s4, v69
	s_waitcnt lgkmcnt(1)
	v_add_f32_e32 v69, v70, v190
	v_or_b32_e32 v70, 10, v174
	v_cndmask_b32_e32 v68, v173, v68, vcc
	v_cmp_gt_u32_e32 vcc, s4, v70
	v_add_f32_e32 v70, v71, v191
	v_or_b32_e32 v71, 11, v174
	ds_read2_b32 v[180:181], v175 offset0:49 offset1:50
	ds_read2_b32 v[182:183], v175 offset0:55 offset1:56
	ds_read2_b32 v[184:185], v175 offset0:57 offset1:58
	v_cndmask_b32_e32 v69, v173, v69, vcc
	v_cmp_gt_u32_e32 vcc, s4, v71
	s_waitcnt lgkmcnt(3)
	v_add_f32_e32 v71, v72, v178
	v_or_b32_e32 v72, 16, v174
	v_cndmask_b32_e32 v70, v173, v70, vcc
	v_cmp_gt_u32_e32 vcc, s4, v72
	v_add_f32_e32 v72, v73, v179
	v_or_b32_e32 v73, 17, v174
	v_cndmask_b32_e32 v71, v173, v71, vcc
	v_cmp_gt_u32_e32 vcc, s4, v73
	s_waitcnt lgkmcnt(2)
	v_add_f32_e32 v73, v74, v180
	v_or_b32_e32 v74, 18, v174
	v_cndmask_b32_e32 v72, v173, v72, vcc
	v_cmp_gt_u32_e32 vcc, s4, v74
	v_add_f32_e32 v74, v75, v181
	v_or_b32_e32 v75, 19, v174
	v_max3_f32 v177, v64, s29, v65
	v_cndmask_b32_e32 v73, v173, v73, vcc
	v_cmp_gt_u32_e32 vcc, s4, v75
	v_max3_f32 v177, v177, v66, v176
	v_max3_f32 v177, v177, v67, v68
	v_cndmask_b32_e32 v75, v173, v74, vcc
	s_waitcnt lgkmcnt(1)
	v_add_f32_e32 v74, v76, v182
	v_or_b32_e32 v76, 24, v174
	v_cmp_gt_u32_e32 vcc, s4, v76
	v_add_f32_e32 v76, v77, v183
	v_or_b32_e32 v77, 25, v174
	v_max3_f32 v177, v177, v69, v70
	v_cndmask_b32_e32 v74, v173, v74, vcc
	v_cmp_gt_u32_e32 vcc, s4, v77
	s_waitcnt lgkmcnt(0)
	v_add_f32_e32 v77, v78, v184
	v_or_b32_e32 v78, 26, v174
	ds_read2_b32 v[178:179], v175 offset0:63 offset1:64
	v_max3_f32 v177, v177, v71, v72
	v_cndmask_b32_e32 v76, v173, v76, vcc
	v_cmp_gt_u32_e32 vcc, s4, v78
	v_add_f32_e32 v78, v79, v185
	v_or_b32_e32 v79, 27, v174
	v_max3_f32 v177, v177, v73, v75
	v_cndmask_b32_e32 v77, v173, v77, vcc
	v_cmp_gt_u32_e32 vcc, s4, v79
	v_max3_f32 v177, v177, v74, v76
	s_waitcnt lgkmcnt(0)
	v_add_f32_e32 v48, v48, v178
	v_cndmask_b32_e32 v78, v173, v78, vcc
	v_max3_f32 v79, v177, v77, v78
	v_add_u32_e32 v177, 32, v174
	v_cmp_gt_u32_e32 vcc, s4, v177
	v_add_u32_e32 v177, 33, v174
	ds_read2_b32 v[180:181], v175 offset0:65 offset1:66
	ds_read2_b32 v[182:183], v175 offset0:71 offset1:72
	ds_read2_b32 v[184:185], v175 offset0:73 offset1:74
	v_cndmask_b32_e32 v48, v173, v48, vcc
	v_add_f32_e32 v49, v49, v179
	v_cmp_gt_u32_e32 vcc, s4, v177
	s_waitcnt lgkmcnt(2)
	v_add_f32_e32 v50, v50, v180
	v_add_f32_e32 v51, v51, v181
	v_cndmask_b32_e32 v49, v173, v49, vcc
	v_max3_f32 v177, v79, v48, v49
	v_add_u32_e32 v79, 34, v174
	v_cmp_gt_u32_e32 vcc, s4, v79
	v_add_u32_e32 v79, 35, v174
	ds_read2_b32 v[178:179], v175 offset0:79 offset1:80
	v_cndmask_b32_e32 v50, v173, v50, vcc
	v_cmp_gt_u32_e32 vcc, s4, v79
	v_mfma_f32_32x32x16_bf16 v[0:15], v[202:205], v[186:189], v[0:15]
	s_nop 0
	v_cndmask_b32_e32 v79, v173, v51, vcc
	s_waitcnt lgkmcnt(2)
	v_add_f32_e32 v51, v52, v182
	v_add_u32_e32 v52, 40, v174
	v_cmp_gt_u32_e32 vcc, s4, v52
	v_add_f32_e32 v52, v53, v183
	v_add_u32_e32 v53, 41, v174
	v_cndmask_b32_e32 v51, v173, v51, vcc
	v_cmp_gt_u32_e32 vcc, s4, v53
	s_waitcnt lgkmcnt(1)
	v_add_f32_e32 v53, v54, v184
	v_add_u32_e32 v54, 42, v174
	v_cndmask_b32_e32 v52, v173, v52, vcc
	v_cmp_gt_u32_e32 vcc, s4, v54
	v_add_f32_e32 v54, v55, v185
	v_add_u32_e32 v55, 43, v174
	ds_read2_b32 v[180:181], v175 offset0:81 offset1:82
	ds_read2_b32 v[182:183], v175 offset0:87 offset1:88
	ds_read2_b32 v[184:185], v175 offset0:89 offset1:90
	v_cndmask_b32_e32 v53, v173, v53, vcc
	v_cmp_gt_u32_e32 vcc, s4, v55
	s_waitcnt lgkmcnt(3)
	v_add_f32_e32 v55, v56, v178
	v_add_u32_e32 v56, 48, v174
	v_cndmask_b32_e32 v54, v173, v54, vcc
	v_cmp_gt_u32_e32 vcc, s4, v56
	v_add_f32_e32 v56, v57, v179
	v_add_u32_e32 v57, 49, v174
	v_cndmask_b32_e32 v55, v173, v55, vcc
	v_cmp_gt_u32_e32 vcc, s4, v57
	s_waitcnt lgkmcnt(2)
	v_add_f32_e32 v57, v58, v180
	v_add_u32_e32 v58, 50, v174
	v_cndmask_b32_e32 v56, v173, v56, vcc
	v_cmp_gt_u32_e32 vcc, s4, v58
	v_add_f32_e32 v58, v59, v181
	v_add_u32_e32 v59, 51, v174
	v_cndmask_b32_e32 v57, v173, v57, vcc
	v_cmp_gt_u32_e32 vcc, s4, v59
	v_max3_f32 v177, v177, v50, v79
	v_max3_f32 v177, v177, v51, v52
	v_cndmask_b32_e32 v59, v173, v58, vcc
	s_waitcnt lgkmcnt(1)
	v_add_f32_e32 v58, v60, v182
	v_add_u32_e32 v60, 56, v174
	v_cmp_gt_u32_e32 vcc, s4, v60
	v_add_f32_e32 v60, v61, v183
	v_add_u32_e32 v61, 57, v174
	v_max3_f32 v177, v177, v53, v54
	v_cndmask_b32_e32 v58, v173, v58, vcc
	v_cmp_gt_u32_e32 vcc, s4, v61
	s_waitcnt lgkmcnt(0)
	v_add_f32_e32 v61, v62, v184
	v_add_u32_e32 v62, 58, v174
	ds_read2_b32 v[178:179], v175 offset0:95 offset1:96
	v_max3_f32 v177, v177, v55, v56
	v_cndmask_b32_e32 v60, v173, v60, vcc
	v_cmp_gt_u32_e32 vcc, s4, v62
	v_add_f32_e32 v62, v63, v185
	v_add_u32_e32 v63, 59, v174
	v_max3_f32 v177, v177, v57, v59
	v_cndmask_b32_e32 v61, v173, v61, vcc
	v_cmp_gt_u32_e32 vcc, s4, v63
	v_max3_f32 v177, v177, v58, v60
	ds_read2_b32 v[180:181], v175 offset0:97 offset1:98
	ds_read2_b32 v[182:183], v175 offset0:103 offset1:104
	ds_read2_b32 v[184:185], v175 offset0:105 offset1:106
	v_cndmask_b32_e32 v62, v173, v62, vcc
	v_max3_f32 v63, v177, v61, v62
	v_add_u32_e32 v177, 64, v174
	s_waitcnt lgkmcnt(3)
	v_add_f32_e32 v32, v32, v178
	v_cmp_gt_u32_e32 vcc, s4, v177
	s_nop 1
	v_cndmask_b32_e32 v177, v173, v32, vcc
	v_add_f32_e32 v32, v33, v179
	v_add_u32_e32 v33, 0x41, v174
	v_cmp_gt_u32_e32 vcc, s4, v33
	s_waitcnt lgkmcnt(2)
	v_add_f32_e32 v33, v34, v180
	v_add_u32_e32 v34, 0x42, v174
	v_cndmask_b32_e32 v178, v173, v32, vcc
	v_cmp_gt_u32_e32 vcc, s4, v34
	v_add_u32_e32 v34, 0x43, v174
	v_max3_f32 v32, v63, v177, v178
	v_cndmask_b32_e32 v63, v173, v33, vcc
	v_add_f32_e32 v33, v35, v181
	v_cmp_gt_u32_e32 vcc, s4, v34
	v_add_u32_e32 v34, 0x48, v174
	s_nop 0
	v_cndmask_b32_e32 v179, v173, v33, vcc
	s_waitcnt lgkmcnt(1)
	v_add_f32_e32 v33, v36, v182
	v_cmp_gt_u32_e32 vcc, s4, v34
	v_add_u32_e32 v34, 0x49, v174
	v_max3_f32 v32, v32, v63, v179
	v_cndmask_b32_e32 v180, v173, v33, vcc
	v_add_f32_e32 v33, v37, v183
	v_cmp_gt_u32_e32 vcc, s4, v34
	s_nop 1
	v_cndmask_b32_e32 v181, v173, v33, vcc
	v_add_u32_e32 v33, 0x4a, v174
	v_max3_f32 v34, v32, v180, v181
	s_waitcnt lgkmcnt(0)
	v_add_f32_e32 v32, v38, v184
	v_cmp_gt_u32_e32 vcc, s4, v33
	v_add_u32_e32 v33, 0x4b, v174
	s_nop 0
	v_cndmask_b32_e32 v182, v173, v32, vcc
	v_add_f32_e32 v32, v39, v185
	v_cmp_gt_u32_e32 vcc, s4, v33
	s_nop 1
	v_cndmask_b32_e32 v183, v173, v32, vcc
	ds_read2_b32 v[32:33], v175 offset0:111 offset1:112
	v_max3_f32 v184, v34, v182, v183
	ds_read2_b32 v[34:35], v175 offset0:113 offset1:114
	ds_read2_b32 v[36:37], v175 offset0:119 offset1:120
	ds_read2_b32 v[38:39], v175 offset0:121 offset1:122
	s_waitcnt lgkmcnt(3)
	v_add_f32_e32 v32, v40, v32
	v_add_u32_e32 v40, 0x50, v174
	v_cmp_gt_u32_e32 vcc, s4, v40
	s_nop 1
	v_cndmask_b32_e32 v185, v173, v32, vcc
	v_add_f32_e32 v32, v41, v33
	v_add_u32_e32 v33, 0x51, v174
	v_cmp_gt_u32_e32 vcc, s4, v33
	s_waitcnt lgkmcnt(2)
	v_add_f32_e32 v33, v42, v34
	v_add_u32_e32 v34, 0x52, v174
	v_cndmask_b32_e32 v186, v173, v32, vcc
	v_cmp_gt_u32_e32 vcc, s4, v34
	v_add_u32_e32 v34, 0x53, v174
	v_max3_f32 v32, v184, v185, v186
	v_cndmask_b32_e32 v42, v173, v33, vcc
	v_add_f32_e32 v33, v43, v35
	v_cmp_gt_u32_e32 vcc, s4, v34
	v_add_u32_e32 v34, 0x58, v174
	s_nop 0
	v_cndmask_b32_e32 v43, v173, v33, vcc
	s_waitcnt lgkmcnt(1)
	v_add_f32_e32 v33, v44, v36
	v_cmp_gt_u32_e32 vcc, s4, v34
	v_add_u32_e32 v34, 0x59, v174
	v_max3_f32 v32, v32, v42, v43
	v_cndmask_b32_e32 v44, v173, v33, vcc
	v_add_f32_e32 v33, v45, v37
	v_cmp_gt_u32_e32 vcc, s4, v34
	s_nop 1
	v_cndmask_b32_e32 v45, v173, v33, vcc
	v_add_u32_e32 v33, 0x5a, v174
	v_max3_f32 v34, v32, v44, v45
	s_waitcnt lgkmcnt(0)
	v_add_f32_e32 v32, v46, v38
	v_cmp_gt_u32_e32 vcc, s4, v33
	v_add_u32_e32 v33, 0x5b, v174
	s_nop 0
	v_cndmask_b32_e32 v46, v173, v32, vcc
	v_add_f32_e32 v32, v47, v39
	v_cmp_gt_u32_e32 vcc, s4, v33
	s_nop 1
	v_cndmask_b32_e32 v47, v173, v32, vcc
	ds_read2_b32 v[32:33], v175 offset0:127 offset1:128
	v_max3_f32 v40, v34, v46, v47
	ds_read2_b32 v[34:35], v175 offset0:129 offset1:130
	ds_read2_b32 v[36:37], v175 offset0:135 offset1:136
	ds_read2_b32 v[38:39], v175 offset0:137 offset1:138
	s_waitcnt lgkmcnt(3)
	v_add_f32_e32 v16, v16, v32
	v_add_u32_e32 v32, 0x60, v174
	v_cmp_gt_u32_e32 vcc, s4, v32
	s_nop 1
	v_cndmask_b32_e32 v184, v173, v16, vcc
	v_add_f32_e32 v16, v17, v33
	v_add_u32_e32 v17, 0x61, v174
	v_cmp_gt_u32_e32 vcc, s4, v17
	s_waitcnt lgkmcnt(2)
	v_add_f32_e32 v17, v18, v34
	v_add_u32_e32 v18, 0x62, v174
	v_cndmask_b32_e32 v187, v173, v16, vcc
	v_cmp_gt_u32_e32 vcc, s4, v18
	v_add_u32_e32 v18, 0x63, v174
	v_max3_f32 v16, v40, v184, v187
	v_cndmask_b32_e32 v188, v173, v17, vcc
	v_add_f32_e32 v17, v19, v35
	v_cmp_gt_u32_e32 vcc, s4, v18
	v_add_u32_e32 v18, 0x68, v174
	s_nop 0
	v_cndmask_b32_e32 v189, v173, v17, vcc
	s_waitcnt lgkmcnt(1)
	v_add_f32_e32 v17, v20, v36
	v_cmp_gt_u32_e32 vcc, s4, v18
	v_add_u32_e32 v18, 0x69, v174
	v_max3_f32 v16, v16, v188, v189
	v_cndmask_b32_e32 v190, v173, v17, vcc
	v_add_f32_e32 v17, v21, v37
	v_cmp_gt_u32_e32 vcc, s4, v18
	s_nop 1
	v_cndmask_b32_e32 v191, v173, v17, vcc
	v_add_u32_e32 v17, 0x6a, v174
	v_max3_f32 v18, v16, v190, v191
	s_waitcnt lgkmcnt(0)
	v_add_f32_e32 v16, v22, v38
	v_cmp_gt_u32_e32 vcc, s4, v17
	v_add_u32_e32 v17, 0x6b, v174
	s_nop 0
	v_cndmask_b32_e32 v192, v173, v16, vcc
	v_add_f32_e32 v16, v23, v39
	v_cmp_gt_u32_e32 vcc, s4, v17
	s_nop 1
	v_cndmask_b32_e32 v193, v173, v16, vcc
	ds_read2_b32 v[16:17], v175 offset0:143 offset1:144
	v_max3_f32 v32, v18, v192, v193
	ds_read2_b32 v[18:19], v175 offset0:145 offset1:146
	ds_read2_b32 v[20:21], v175 offset0:151 offset1:152
	ds_read2_b32 v[22:23], v175 offset0:153 offset1:154
	s_waitcnt lgkmcnt(3)
	v_add_f32_e32 v16, v24, v16
	v_add_u32_e32 v24, 0x70, v174
	v_cmp_gt_u32_e32 vcc, s4, v24
	s_nop 1
	v_cndmask_b32_e32 v24, v173, v16, vcc
	v_add_f32_e32 v16, v25, v17
	v_add_u32_e32 v17, 0x71, v174
	v_cmp_gt_u32_e32 vcc, s4, v17
	s_waitcnt lgkmcnt(2)
	v_add_f32_e32 v17, v26, v18
	v_add_u32_e32 v18, 0x72, v174
	v_cndmask_b32_e32 v25, v173, v16, vcc
	v_cmp_gt_u32_e32 vcc, s4, v18
	v_add_u32_e32 v18, 0x73, v174
	v_max3_f32 v16, v32, v24, v25
	v_cndmask_b32_e32 v26, v173, v17, vcc
	v_add_f32_e32 v17, v27, v19
	v_cmp_gt_u32_e32 vcc, s4, v18
	v_add_u32_e32 v18, 0x78, v174
	s_nop 0
	v_cndmask_b32_e32 v27, v173, v17, vcc
	s_waitcnt lgkmcnt(1)
	v_add_f32_e32 v17, v28, v20
	v_cmp_gt_u32_e32 vcc, s4, v18
	v_add_u32_e32 v18, 0x79, v174
	v_max3_f32 v16, v16, v26, v27
	v_cndmask_b32_e32 v28, v173, v17, vcc
	v_add_f32_e32 v17, v29, v21
	v_cmp_gt_u32_e32 vcc, s4, v18
	s_nop 1
	v_cndmask_b32_e32 v29, v173, v17, vcc
	v_add_u32_e32 v17, 0x7a, v174
	v_max3_f32 v18, v16, v28, v29
	s_waitcnt lgkmcnt(0)
	v_add_f32_e32 v16, v30, v22
	v_cmp_gt_u32_e32 vcc, s4, v17
	v_add_u32_e32 v17, 0x7b, v174
	s_nop 0
	v_cndmask_b32_e32 v30, v173, v16, vcc
	v_add_f32_e32 v16, v31, v23
	v_cmp_gt_u32_e32 vcc, s4, v17
	s_nop 1
	v_cndmask_b32_e32 v194, v173, v16, vcc
	ds_read2_b32 v[16:17], v175 offset0:159 offset1:160
	v_max3_f32 v31, v18, v30, v194
	ds_read2_b32 v[18:19], v175 offset0:161 offset1:162
	ds_read2_b32 v[20:21], v175 offset0:167 offset1:168
	ds_read2_b32 v[22:23], v175 offset0:169 offset1:170
	s_waitcnt lgkmcnt(3)
	v_add_f32_e32 v0, v0, v16
	v_add_u32_e32 v16, 0x80, v174
	v_cmp_gt_u32_e32 vcc, s4, v16
	s_nop 1
	v_cndmask_b32_e32 v195, v173, v0, vcc
	v_add_f32_e32 v0, v1, v17
	v_add_u32_e32 v1, 0x81, v174
	v_cmp_gt_u32_e32 vcc, s4, v1
	s_waitcnt lgkmcnt(2)
	v_add_f32_e32 v1, v2, v18
	v_add_u32_e32 v2, 0x82, v174
	v_cndmask_b32_e32 v196, v173, v0, vcc
	v_cmp_gt_u32_e32 vcc, s4, v2
	v_add_u32_e32 v2, 0x83, v174
	v_max3_f32 v0, v31, v195, v196
	v_cndmask_b32_e32 v197, v173, v1, vcc
	v_add_f32_e32 v1, v3, v19
	v_cmp_gt_u32_e32 vcc, s4, v2
	v_add_u32_e32 v2, 0x88, v174
	s_nop 0
	v_cndmask_b32_e32 v198, v173, v1, vcc
	s_waitcnt lgkmcnt(1)
	v_add_f32_e32 v1, v4, v20
	v_cmp_gt_u32_e32 vcc, s4, v2
	v_add_u32_e32 v2, 0x89, v174
	v_max3_f32 v0, v0, v197, v198
	v_cndmask_b32_e32 v199, v173, v1, vcc
	v_add_f32_e32 v1, v5, v21
	v_cmp_gt_u32_e32 vcc, s4, v2
	s_nop 1
	v_cndmask_b32_e32 v200, v173, v1, vcc
	v_add_u32_e32 v1, 0x8a, v174
	v_max3_f32 v2, v0, v199, v200
	s_waitcnt lgkmcnt(0)
	v_add_f32_e32 v0, v6, v22
	v_cmp_gt_u32_e32 vcc, s4, v1
	v_add_u32_e32 v1, 0x8b, v174
	s_nop 0
	v_cndmask_b32_e32 v201, v173, v0, vcc
	v_add_f32_e32 v0, v7, v23
	v_cmp_gt_u32_e32 vcc, s4, v1
	s_nop 1
	v_cndmask_b32_e32 v38, v173, v0, vcc
	ds_read2_b32 v[0:1], v175 offset0:175 offset1:176
	v_max3_f32 v16, v2, v201, v38
	ds_read2_b32 v[2:3], v175 offset0:177 offset1:178
	ds_read2_b32 v[4:5], v175 offset0:183 offset1:184
	ds_read2_b32 v[6:7], v175 offset0:185 offset1:186
	s_waitcnt lgkmcnt(3)
	v_add_f32_e32 v0, v8, v0
	v_add_u32_e32 v8, 0x90, v174
	v_cmp_gt_u32_e32 vcc, s4, v8
	s_nop 1
	v_cndmask_b32_e32 v39, v173, v0, vcc
	v_add_f32_e32 v0, v9, v1
	v_add_u32_e32 v1, 0x91, v174
	v_cmp_gt_u32_e32 vcc, s4, v1
	s_waitcnt lgkmcnt(2)
	v_add_f32_e32 v1, v10, v2
	v_add_u32_e32 v2, 0x92, v174
	v_cndmask_b32_e32 v40, v173, v0, vcc
	v_cmp_gt_u32_e32 vcc, s4, v2
	v_add_u32_e32 v2, 0x93, v174
	v_max3_f32 v0, v16, v39, v40
	v_cndmask_b32_e32 v41, v173, v1, vcc
	v_add_f32_e32 v1, v11, v3
	v_cmp_gt_u32_e32 vcc, s4, v2
	v_add_u32_e32 v2, 0x98, v174
	s_nop 0
	v_cndmask_b32_e32 v37, v173, v1, vcc
	s_waitcnt lgkmcnt(1)
	v_add_f32_e32 v1, v12, v4
	v_cmp_gt_u32_e32 vcc, s4, v2
	v_add_u32_e32 v2, 0x99, v174
	v_max3_f32 v0, v0, v41, v37
	v_cndmask_b32_e32 v33, v173, v1, vcc
	v_add_f32_e32 v1, v13, v5
	v_cmp_gt_u32_e32 vcc, s4, v2
	v_add_u32_e32 v2, 0x9a, v174
	s_nop 0
	v_cndmask_b32_e32 v35, v173, v1, vcc
	s_waitcnt lgkmcnt(0)
	v_add_f32_e32 v1, v14, v6
	v_cmp_gt_u32_e32 vcc, s4, v2
	v_add_u32_e32 v2, 0x9b, v174
	v_max3_f32 v0, v0, v33, v35
	v_cndmask_b32_e32 v36, v173, v1, vcc
	v_add_f32_e32 v1, v15, v7
	v_cmp_gt_u32_e32 vcc, s4, v2
	s_nop 1
	v_cndmask_b32_e32 v32, v173, v1, vcc
	v_max3_f32 v0, v0, v36, v32
	ds_bpermute_b32 v1, v160, v0
	s_waitcnt lgkmcnt(0)
	v_max_f32_e32 v1, v1, v1
	v_max_f32_e32 v34, v0, v1
	v_sub_f32_e32 v0, v64, v34
	v_exp_f32_e32 v4, v0
	v_sub_f32_e32 v0, v65, v34
	v_exp_f32_e32 v5, v0
	v_sub_f32_e32 v0, v66, v34
	v_exp_f32_e32 v6, v0
	v_sub_f32_e32 v0, v176, v34
	v_exp_f32_e32 v7, v0
	v_sub_f32_e32 v1, v67, v34
	v_add_f32_e32 v0, 0, v4
	v_exp_f32_e32 v8, v1
	v_sub_f32_e32 v1, v68, v34
	v_add_f32_e32 v0, v5, v0
	v_exp_f32_e32 v9, v1
	v_sub_f32_e32 v1, v69, v34
	v_add_f32_e32 v0, v6, v0
	v_exp_f32_e32 v10, v1
	v_sub_f32_e32 v1, v70, v34
	v_add_f32_e32 v0, v7, v0
	v_exp_f32_e32 v11, v1
	v_sub_f32_e32 v1, v71, v34
	v_add_f32_e32 v0, v8, v0
	v_exp_f32_e32 v64, v1
	v_sub_f32_e32 v1, v72, v34
	v_add_f32_e32 v0, v9, v0
	v_exp_f32_e32 v65, v1
	v_sub_f32_e32 v1, v73, v34
	v_add_f32_e32 v0, v10, v0
	v_exp_f32_e32 v66, v1
	v_sub_f32_e32 v1, v75, v34
	v_add_f32_e32 v0, v11, v0
	v_exp_f32_e32 v67, v1
	v_sub_f32_e32 v1, v74, v34
	v_add_f32_e32 v0, v64, v0
	v_exp_f32_e32 v68, v1
	v_sub_f32_e32 v1, v76, v34
	v_add_f32_e32 v0, v65, v0
	v_exp_f32_e32 v69, v1
	v_sub_f32_e32 v1, v77, v34
	v_add_f32_e32 v0, v66, v0
	v_exp_f32_e32 v70, v1
	v_sub_f32_e32 v1, v78, v34
	v_add_f32_e32 v0, v67, v0
	v_exp_f32_e32 v71, v1
	v_sub_f32_e32 v1, v48, v34
	v_add_f32_e32 v0, v68, v0
	v_exp_f32_e32 v72, v1
	v_sub_f32_e32 v1, v49, v34
	v_add_f32_e32 v0, v69, v0
	v_exp_f32_e32 v73, v1
	v_sub_f32_e32 v1, v50, v34
	v_add_f32_e32 v0, v70, v0
	v_exp_f32_e32 v74, v1
	v_sub_f32_e32 v1, v79, v34
	v_add_f32_e32 v0, v71, v0
	v_exp_f32_e32 v75, v1
	v_sub_f32_e32 v1, v51, v34
	v_add_f32_e32 v0, v72, v0
	v_exp_f32_e32 v76, v1
	v_sub_f32_e32 v1, v52, v34
	v_add_f32_e32 v0, v73, v0
	v_exp_f32_e32 v77, v1
	v_sub_f32_e32 v1, v53, v34
	v_add_f32_e32 v0, v74, v0
	v_exp_f32_e32 v78, v1
	v_sub_f32_e32 v1, v54, v34
	v_add_f32_e32 v0, v75, v0
	v_exp_f32_e32 v54, v1
	v_sub_f32_e32 v1, v55, v34
	v_add_f32_e32 v0, v76, v0
	v_exp_f32_e32 v55, v1
	v_sub_f32_e32 v1, v56, v34
	v_add_f32_e32 v0, v77, v0
	v_exp_f32_e32 v56, v1
	v_sub_f32_e32 v1, v57, v34
	v_add_f32_e32 v0, v78, v0
	v_exp_f32_e32 v57, v1
	v_sub_f32_e32 v1, v59, v34
	v_add_f32_e32 v0, v54, v0
	v_exp_f32_e32 v59, v1
	v_sub_f32_e32 v1, v58, v34
	v_add_f32_e32 v0, v55, v0
	v_exp_f32_e32 v58, v1
	v_sub_f32_e32 v1, v60, v34
	v_add_f32_e32 v0, v56, v0
	v_exp_f32_e32 v60, v1
	v_sub_f32_e32 v1, v61, v34
	v_add_f32_e32 v0, v57, v0
	v_exp_f32_e32 v61, v1
	v_sub_f32_e32 v1, v62, v34
	v_add_f32_e32 v0, v59, v0
	v_exp_f32_e32 v62, v1
	v_sub_f32_e32 v1, v177, v34
	v_add_f32_e32 v0, v58, v0
	v_exp_f32_e32 v79, v1
	v_sub_f32_e32 v1, v178, v34
	v_add_f32_e32 v0, v60, v0
	v_exp_f32_e32 v174, v1
	v_sub_f32_e32 v1, v63, v34
	v_add_f32_e32 v0, v61, v0
	v_exp_f32_e32 v63, v1
	v_sub_f32_e32 v1, v179, v34
	v_add_f32_e32 v0, v62, v0
	v_exp_f32_e32 v175, v1
	v_sub_f32_e32 v1, v180, v34
	v_add_f32_e32 v0, v79, v0
	v_exp_f32_e32 v176, v1
	v_sub_f32_e32 v1, v181, v34
	v_add_f32_e32 v0, v174, v0
	v_exp_f32_e32 v177, v1
	v_sub_f32_e32 v1, v182, v34
	v_add_f32_e32 v0, v63, v0
	v_exp_f32_e32 v178, v1
	v_sub_f32_e32 v1, v183, v34
	v_add_f32_e32 v0, v175, v0
	v_exp_f32_e32 v179, v1
	v_sub_f32_e32 v1, v185, v34
	v_add_f32_e32 v0, v176, v0
	v_exp_f32_e32 v180, v1
	v_sub_f32_e32 v1, v186, v34
	v_add_f32_e32 v0, v177, v0
	v_exp_f32_e32 v181, v1
	v_sub_f32_e32 v1, v42, v34
	v_add_f32_e32 v0, v178, v0
	v_exp_f32_e32 v182, v1
	v_sub_f32_e32 v1, v43, v34
	v_add_f32_e32 v0, v179, v0
	v_exp_f32_e32 v183, v1
	v_sub_f32_e32 v1, v44, v34
	v_add_f32_e32 v0, v180, v0
	v_exp_f32_e32 v185, v1
	v_sub_f32_e32 v1, v45, v34
	v_add_f32_e32 v0, v181, v0
	v_exp_f32_e32 v186, v1
	v_sub_f32_e32 v1, v46, v34
	v_add_f32_e32 v0, v182, v0
	v_exp_f32_e32 v202, v1
	v_sub_f32_e32 v1, v47, v34
	v_add_f32_e32 v0, v183, v0
	v_exp_f32_e32 v203, v1
	v_sub_f32_e32 v1, v184, v34
	v_add_f32_e32 v0, v185, v0
	v_exp_f32_e32 v184, v1
	v_sub_f32_e32 v1, v187, v34
	v_add_f32_e32 v0, v186, v0
	v_exp_f32_e32 v187, v1
	v_sub_f32_e32 v1, v188, v34
	v_add_f32_e32 v0, v202, v0
	v_exp_f32_e32 v188, v1
	v_sub_f32_e32 v1, v189, v34
	v_add_f32_e32 v0, v203, v0
	v_exp_f32_e32 v189, v1
	v_sub_f32_e32 v1, v190, v34
	v_add_f32_e32 v0, v184, v0
	v_exp_f32_e32 v190, v1
	v_sub_f32_e32 v1, v191, v34
	v_add_f32_e32 v0, v187, v0
	v_exp_f32_e32 v191, v1
	v_sub_f32_e32 v1, v192, v34
	v_add_f32_e32 v0, v188, v0
	v_exp_f32_e32 v192, v1
	v_sub_f32_e32 v1, v193, v34
	v_add_f32_e32 v0, v189, v0
	v_exp_f32_e32 v193, v1
	v_sub_f32_e32 v1, v24, v34
	v_add_f32_e32 v0, v190, v0
	v_exp_f32_e32 v204, v1
	v_sub_f32_e32 v1, v25, v34
	v_add_f32_e32 v0, v191, v0
	v_exp_f32_e32 v205, v1
	v_sub_f32_e32 v1, v26, v34
	v_add_f32_e32 v0, v192, v0
	v_exp_f32_e32 v206, v1
	v_sub_f32_e32 v1, v27, v34
	v_add_f32_e32 v0, v193, v0
	v_exp_f32_e32 v207, v1
	v_add_f32_e32 v0, v204, v0
	v_add_f32_e32 v0, v205, v0
	v_add_f32_e32 v0, v206, v0
	v_add_f32_e32 v12, v207, v0
	v_sub_f32_e32 v0, v28, v34
	v_exp_f32_e32 v208, v0
	v_sub_f32_e32 v0, v29, v34
	v_exp_f32_e32 v209, v0
	ds_read_b64_tr_b16 v[0:1], v161 offset:64512
	ds_read_b64_tr_b16 v[2:3], v162 offset:1152
	v_sub_f32_e32 v13, v30, v34
	v_exp_f32_e32 v210, v13
	v_cvt_pk_bf16_f32 v4, v4, v5
	v_cvt_pk_bf16_f32 v5, v6, v7
	v_cvt_pk_bf16_f32 v6, v8, v9
	v_cvt_pk_bf16_f32 v7, v10, v11
	ds_read_b64_tr_b16 v[10:11], v162 offset:1216
	ds_read_b64_tr_b16 v[8:9], v161 offset:64576
	s_waitcnt lgkmcnt(2)
	v_mfma_f32_32x32x16_bf16 v[16:31], v[0:3], v[4:7], 0
	v_add_f32_e32 v0, v208, v12
	v_add_f32_e32 v0, v209, v0
	v_add_f32_e32 v46, v210, v0
	v_sub_f32_e32 v0, v194, v34
	v_exp_f32_e32 v194, v0
	ds_read_b64_tr_b16 v[42:43], v162 offset:2304
	ds_read_b64_tr_b16 v[44:45], v162 offset:3456
	v_cvt_pk_bf16_f32 v47, v66, v67
	s_waitcnt lgkmcnt(2)
	v_mfma_f32_32x32x16_bf16 v[0:15], v[8:11], v[4:7], 0
	v_add_f32_e32 v211, v194, v46
	v_cvt_pk_bf16_f32 v46, v64, v65
	v_cvt_pk_bf16_f32 v48, v68, v69
	v_cvt_pk_bf16_f32 v49, v70, v71
	ds_read_b64_tr_b16 v[52:53], v162 offset:3520
	ds_read_b64_tr_b16 v[50:51], v162 offset:2368
	v_sub_f32_e32 v66, v197, v34
	v_exp_f32_e32 v66, v66
	s_waitcnt lgkmcnt(2)
	v_mfma_f32_32x32x16_bf16 v[16:31], v[42:45], v[46:49], v[16:31]
	v_sub_f32_e32 v42, v195, v34
	v_exp_f32_e32 v64, v42
	v_sub_f32_e32 v42, v196, v34
	v_exp_f32_e32 v65, v42
	ds_read_b64_tr_b16 v[42:43], v162 offset:4608
	ds_read_b64_tr_b16 v[44:45], v162 offset:5760
	v_sub_f32_e32 v38, v38, v34
	v_sub_f32_e32 v37, v37, v34
	s_waitcnt lgkmcnt(2)
	v_mfma_f32_32x32x16_bf16 v[0:15], v[50:53], v[46:49], v[0:15]
	v_cvt_pk_bf16_f32 v46, v72, v73
	v_cvt_pk_bf16_f32 v47, v74, v75
	v_cvt_pk_bf16_f32 v48, v76, v77
	v_cvt_pk_bf16_f32 v49, v78, v54
	ds_read_b64_tr_b16 v[52:53], v162 offset:5824
	ds_read_b64_tr_b16 v[50:51], v162 offset:4672
	v_sub_f32_e32 v33, v33, v34
	v_exp_f32_e32 v33, v33
	s_waitcnt lgkmcnt(2)
	v_mfma_f32_32x32x16_bf16 v[16:31], v[42:45], v[46:49], v[16:31]
	v_add_f32_e32 v42, v64, v211
	v_add_f32_e32 v42, v65, v42
	v_add_f32_e32 v54, v66, v42
	v_sub_f32_e32 v42, v198, v34
	v_exp_f32_e32 v67, v42
	ds_read_b64_tr_b16 v[42:43], v162 offset:6912
	ds_read_b64_tr_b16 v[44:45], v162 offset:8064
	v_sub_f32_e32 v35, v35, v34
	s_waitcnt lgkmcnt(2)
	v_mfma_f32_32x32x16_bf16 v[0:15], v[50:53], v[46:49], v[0:15]
	v_cvt_pk_bf16_f32 v46, v55, v56
	v_cvt_pk_bf16_f32 v47, v57, v59
	v_cvt_pk_bf16_f32 v48, v58, v60
	v_cvt_pk_bf16_f32 v49, v61, v62
	ds_read_b64_tr_b16 v[52:53], v162 offset:8128
	ds_read_b64_tr_b16 v[50:51], v162 offset:6976
	v_sub_f32_e32 v57, v201, v34
	v_exp_f32_e32 v57, v57
	s_waitcnt lgkmcnt(2)
	v_mfma_f32_32x32x16_bf16 v[16:31], v[42:45], v[46:49], v[16:31]
	v_sub_f32_e32 v42, v199, v34
	v_exp_f32_e32 v55, v42
	v_sub_f32_e32 v42, v200, v34
	v_exp_f32_e32 v56, v42
	ds_read_b64_tr_b16 v[42:43], v162 offset:9216
	ds_read_b64_tr_b16 v[44:45], v162 offset:10368
	v_add_f32_e32 v54, v67, v54
	v_exp_f32_e32 v58, v38
	s_waitcnt lgkmcnt(2)
	v_mfma_f32_32x32x16_bf16 v[0:15], v[50:53], v[46:49], v[0:15]
	v_cvt_pk_bf16_f32 v46, v79, v174
	v_cvt_pk_bf16_f32 v47, v63, v175
	v_cvt_pk_bf16_f32 v48, v176, v177
	v_cvt_pk_bf16_f32 v49, v178, v179
	ds_read_b64_tr_b16 v[52:53], v162 offset:10432
	ds_read_b64_tr_b16 v[50:51], v162 offset:9280
	v_sub_f32_e32 v38, v39, v34
	v_exp_f32_e32 v59, v38
	s_waitcnt lgkmcnt(2)
	v_mfma_f32_32x32x16_bf16 v[16:31], v[42:45], v[46:49], v[16:31]
	v_add_f32_e32 v42, v55, v54
	v_add_f32_e32 v42, v56, v42
	v_add_f32_e32 v54, v57, v42
	ds_read_b64_tr_b16 v[42:43], v162 offset:11520
	ds_read_b64_tr_b16 v[44:45], v162 offset:12672
	v_sub_f32_e32 v38, v40, v34
	v_exp_f32_e32 v60, v38
	v_add_f32_e32 v54, v58, v54
	s_waitcnt lgkmcnt(2)
	v_mfma_f32_32x32x16_bf16 v[0:15], v[50:53], v[46:49], v[0:15]
	v_cvt_pk_bf16_f32 v46, v180, v181
	v_cvt_pk_bf16_f32 v47, v182, v183
	v_cvt_pk_bf16_f32 v48, v185, v186
	v_cvt_pk_bf16_f32 v49, v202, v203
	ds_read_b64_tr_b16 v[52:53], v162 offset:12736
	ds_read_b64_tr_b16 v[50:51], v162 offset:11584
	v_exp_f32_e32 v35, v35
	v_sub_f32_e32 v32, v32, v34
	s_waitcnt lgkmcnt(2)
	v_mfma_f32_32x32x16_bf16 v[16:31], v[42:45], v[46:49], v[16:31]
	v_sub_f32_e32 v42, v41, v34
	ds_read_b64_tr_b16 v[38:39], v162 offset:13824
	ds_read_b64_tr_b16 v[40:41], v162 offset:14976
	v_cvt_pk_bf16_f32 v43, v188, v189
	v_cvt_pk_bf16_f32 v44, v190, v191
	v_cvt_pk_bf16_f32 v45, v192, v193
	v_exp_f32_e32 v32, v32
	s_waitcnt lgkmcnt(2)
	v_mfma_f32_32x32x16_bf16 v[0:15], v[50:53], v[46:49], v[0:15]
	v_exp_f32_e32 v50, v42
	v_cvt_pk_bf16_f32 v42, v184, v187
	ds_read_b64_tr_b16 v[48:49], v162 offset:15040
	ds_read_b64_tr_b16 v[46:47], v162 offset:13888
	v_exp_f32_e32 v52, v37
	s_waitcnt lgkmcnt(2)
	v_mfma_f32_32x32x16_bf16 v[16:31], v[38:41], v[42:45], v[16:31]
	v_add_f32_e32 v38, v59, v54
	v_add_f32_e32 v38, v60, v38
	v_add_f32_e32 v51, v50, v38
	ds_read_b64_tr_b16 v[38:39], v162 offset:16128
	ds_read_b64_tr_b16 v[40:41], v162 offset:17280
	v_add_f32_e32 v51, v52, v51
	s_waitcnt lgkmcnt(2)
	v_mfma_f32_32x32x16_bf16 v[0:15], v[46:49], v[42:45], v[0:15]
	v_cvt_pk_bf16_f32 v42, v204, v205
	v_cvt_pk_bf16_f32 v43, v206, v207
	v_cvt_pk_bf16_f32 v44, v208, v209
	v_cvt_pk_bf16_f32 v45, v210, v194
	ds_read_b64_tr_b16 v[48:49], v162 offset:17344
	ds_read_b64_tr_b16 v[46:47], v162 offset:16192
	s_waitcnt lgkmcnt(2)
	v_mfma_f32_32x32x16_bf16 v[16:31], v[38:41], v[42:45], v[16:31]
	v_sub_f32_e32 v40, v36, v34
	ds_read_b64_tr_b16 v[36:37], v162 offset:18432
	ds_read_b64_tr_b16 v[38:39], v162 offset:19584
	v_cvt_pk_bf16_f32 v41, v66, v67
	s_waitcnt lgkmcnt(2)
	v_mfma_f32_32x32x16_bf16 v[0:15], v[46:49], v[42:45], v[0:15]
	v_exp_f32_e32 v48, v40
	v_cvt_pk_bf16_f32 v40, v64, v65
	v_cvt_pk_bf16_f32 v42, v55, v56
	v_cvt_pk_bf16_f32 v43, v57, v58
	ds_read_b64_tr_b16 v[46:47], v162 offset:19648
	ds_read_b64_tr_b16 v[44:45], v162 offset:18496
	s_waitcnt lgkmcnt(2)
	v_mfma_f32_32x32x16_bf16 v[16:31], v[36:39], v[40:43], v[16:31]
	v_add_f32_e32 v36, v33, v51
	v_add_f32_e32 v36, v35, v36
	v_add_f32_e32 v49, v48, v36
	v_add_f32_e32 v49, v32, v49
	ds_read_b64_tr_b16 v[36:37], v162 offset:20736
	ds_read_b64_tr_b16 v[38:39], v162 offset:21888
	s_waitcnt lgkmcnt(2)
	v_mfma_f32_32x32x16_bf16 v[0:15], v[44:47], v[40:43], v[0:15]
	v_cvt_pk_bf16_f32 v43, v48, v32
	ds_bpermute_b32 v32, v160, v49
	v_cvt_pk_bf16_f32 v42, v33, v35
	ds_read_b64_tr_b16 v[46:47], v162 offset:21952
	ds_read_b64_tr_b16 v[44:45], v162 offset:20800
	v_cvt_pk_bf16_f32 v40, v59, v60
	v_cvt_pk_bf16_f32 v41, v50, v52
	s_waitcnt lgkmcnt(2)
	v_add_f32_e32 v35, v49, v32
	v_div_scale_f32 v32, s[4:5], v35, v35, 1.0
	v_rcp_f32_e32 v33, v32
	v_mfma_f32_32x32x16_bf16 v[16:31], v[36:39], v[40:43], v[16:31]
	s_ashr_i32 s4, s3, 31
	s_ashr_i32 s5, s14, 31
	v_fma_f32 v36, -v32, v33, 1.0
	v_fmac_f32_e32 v33, v36, v33
	v_div_scale_f32 v36, vcc, 1.0, v35, 1.0
	v_mul_f32_e32 v37, v36, v33
	s_waitcnt lgkmcnt(0)
	v_mfma_f32_32x32x16_bf16 v[0:15], v[44:47], v[40:43], v[0:15]
	v_fma_f32 v38, -v32, v37, v36
	v_fmac_f32_e32 v37, v38, v33
	v_fma_f32 v32, -v32, v37, v36
	v_div_fmas_f32 v32, v32, v33, v37
	v_div_fixup_f32 v36, v32, v35, 1.0
	v_add_u32_e32 v32, s31, v155
	v_ashrrev_i32_e32 v33, 31, v32
	s_add_u32 s9, s3, s14
	v_lshlrev_b64 v[32:33], s30, v[32:33]
	s_addc_u32 s3, s4, s5
	s_or_b32 s2, s9, s2
	v_lshl_add_u64 v[32:33], s[2:3], 0, v[32:33]
	v_lshlrev_b64 v[38:39], 9, v[32:33]
	v_pk_mul_f32 v[16:17], v[16:17], v[36:37] op_sel_hi:[1,0]
	v_pk_mul_f32 v[18:19], v[18:19], v[36:37] op_sel_hi:[1,0]
	v_pk_mul_f32 v[0:1], v[0:1], v[36:37] op_sel_hi:[1,0]
	v_pk_mul_f32 v[2:3], v[2:3], v[36:37] op_sel_hi:[1,0]
	v_lshl_add_u64 v[38:39], s[18:19], 0, v[38:39]
	s_lshl_b32 s14, s8, 7
	v_cvt_pk_bf16_f32 v16, v16, v17
	v_cvt_pk_bf16_f32 v17, v18, v19
	v_pk_mul_f32 v[18:19], v[20:21], v[36:37] op_sel_hi:[1,0]
	v_pk_mul_f32 v[20:21], v[22:23], v[36:37] op_sel_hi:[1,0]
	v_cvt_pk_bf16_f32 v0, v0, v1
	v_cvt_pk_bf16_f32 v1, v2, v3
	v_pk_mul_f32 v[2:3], v[4:5], v[36:37] op_sel_hi:[1,0]
	v_pk_mul_f32 v[4:5], v[6:7], v[36:37] op_sel_hi:[1,0]
	v_lshl_add_u64 v[38:39], v[38:39], 0, s[14:15]
	v_cvt_pk_bf16_f32 v18, v18, v19
	v_cvt_pk_bf16_f32 v19, v20, v21
	v_cvt_pk_bf16_f32 v2, v2, v3
	v_cvt_pk_bf16_f32 v3, v4, v5
	v_permlane32_swap_b32_e32 v16, v18
	v_permlane32_swap_b32_e32 v17, v19
	v_lshl_add_u64 v[20:21], v[38:39], 0, v[144:145]
	v_permlane32_swap_b32_e32 v0, v2
	v_permlane32_swap_b32_e32 v1, v3
	global_store_dwordx4 v[20:21], v[16:19], off
	global_store_dwordx4 v[20:21], v[0:3], off offset:64
	v_pk_mul_f32 v[22:23], v[30:31], v[36:37] op_sel_hi:[1,0]
	v_pk_mul_f32 v[16:17], v[24:25], v[36:37] op_sel_hi:[1,0]
	v_pk_mul_f32 v[18:19], v[26:27], v[36:37] op_sel_hi:[1,0]
	v_pk_mul_f32 v[0:1], v[8:9], v[36:37] op_sel_hi:[1,0]
	v_pk_mul_f32 v[2:3], v[10:11], v[36:37] op_sel_hi:[1,0]
	v_cvt_pk_bf16_f32 v16, v16, v17
	v_cvt_pk_bf16_f32 v17, v18, v19
	v_pk_mul_f32 v[18:19], v[28:29], v[36:37] op_sel_hi:[1,0]
	v_cvt_pk_bf16_f32 v0, v0, v1
	v_cvt_pk_bf16_f32 v1, v2, v3
	v_pk_mul_f32 v[2:3], v[12:13], v[36:37] op_sel_hi:[1,0]
	v_pk_mul_f32 v[4:5], v[14:15], v[36:37] op_sel_hi:[1,0]
	v_cvt_pk_bf16_f32 v18, v18, v19
	v_cvt_pk_bf16_f32 v19, v22, v23
	v_cvt_pk_bf16_f32 v2, v2, v3
	v_cvt_pk_bf16_f32 v3, v4, v5
	v_permlane32_swap_b32_e32 v16, v18
	v_permlane32_swap_b32_e32 v17, v19
	v_permlane32_swap_b32_e32 v0, v2
	v_permlane32_swap_b32_e32 v1, v3
	global_store_dwordx4 v[20:21], v[16:19], off offset:32
	global_store_dwordx4 v[20:21], v[0:3], off offset:96
	s_and_saveexec_b64 s[2:3], s[6:7]
	s_cbranch_execz .LBB0_385
	v_log_f32_e32 v2, v35
	v_lshl_add_u64 v[0:1], v[32:33], 4, s[24:25]
	s_lshl_b32 s14, s8, 2
	v_lshl_add_u64 v[0:1], v[0:1], 0, s[14:15]
	v_add_f32_e32 v2, v34, v2
	v_mul_f32_e32 v2, 0x3f317218, v2
	global_store_dword v[0:1], v2, off
	s_branch .LBB0_385
